# 5b1: token-row loads issued before the gathers, compute on rows 0-63 starts while rows 64-127 are in flight (counted vmcnt)
# speedup vs baseline: 1.0080x; 1.0049x over previous
; DI long mk64(unsigned lo, unsigned hi) { return (long)(((unsigned long)hi << 32) | lo); }
; DI void phase5b1(const Params& p, u16* smem) {
;     ...
;   for (;;) {
;     *(unsigned*)(escr + lane * 2) = erow;
; #pragma unroll
;     for (int g = 0; g < 16; ++g) e[g] = escr[g * 8 + r8];
;     asm volatile("s_waitcnt lgkmcnt(0)" ::: "memory");
; #pragma unroll
;     for (int g = 0; g < 16; ++g)
;       __builtin_amdgcn_global_load_lds((const unsigned*)(U8 + (size_t)(unsigned)((e[g] << 7) + ch * 16)), (unsigned*)(lds + g * 1024), 16, 0, 0);
;     const uint4 hb0 = *(const uint4*)(H8 + (size_t)(unsigned)(t * 1024));
;     const uint4 hb1 = *(const uint4*)(H8 + (size_t)(unsigned)(t * 1024 + 16));
;     const int tnx = t + stride;
;     const bool more = tnx < T_ALL;
;     erow = *(const unsigned*)(sele + (size_t)(unsigned)((more ? tnx : t) * 128 + lane * 2));
;     asm volatile("s_waitcnt vmcnt(0)" ::: "memory");
;     const long b0 = mk64(hb0.x, hb0.y), b1 = mk64(hb0.z, hb0.w), b2 = mk64(hb1.x, hb1.y), b3 = mk64(hb1.z, hb1.w);
; #pragma unroll
;     for (int pt = 0; pt < 8; ++pt) {
;       const uint4 a0 = *(const uint4*)(lds + (pt * 16 + l16) * 128 + quad * 32);
;       const uint4 a1 = *(const uint4*)(lds + (pt * 16 + l16) * 128 + quad * 32 + 16);
;       f32x4 acc = {0.f, 0.f, 0.f, 0.f};
;       acc = __builtin_amdgcn_mfma_f32_16x16x32_fp8_fp8(mk64(a0.x, a0.y), b0, acc, 0, 0, 0);
;       acc = __builtin_amdgcn_mfma_f32_16x16x32_fp8_fp8(mk64(a0.z, a0.w), b1, acc, 0, 0, 0);
;       acc = __builtin_amdgcn_mfma_f32_16x16x32_fp8_fp8(mk64(a1.x, a1.y), b2, acc, 0, 0, 0);
;       acc = __builtin_amdgcn_mfma_f32_16x16x32_fp8_fp8(mk64(a1.z, a1.w), b3, acc, 0, 0, 0);
;       if (l16 == 0) { uint2 pk2; pk2.x = pack2(acc[0], acc[1]); pk2.y = pack2(acc[2], acc[3]); *(uint2*)(part + (size_t)(unsigned)(t * 128 + pt * 16 + quad * 4)) = pk2; }
;     }
.LBB0_373:
	s_waitcnt vmcnt(8)
	v_lshl_add_u64 v[132:133], v[14:15], 0, s[22:23]
	global_load_dwordx4 v[134:137], v[132:133], off offset:16
	global_load_dwordx4 v[138:141], v[132:133], off
	ds_write_b32 v19, v23
	ds_read_u16 v0, v20
	ds_read_u16 v1, v20 offset:16
	ds_read_u16 v2, v20 offset:32
	ds_read_u16 v3, v20 offset:48
	ds_read_u16 v4, v20 offset:64
	ds_read_u16 v5, v20 offset:80
	ds_read_u16 v6, v20 offset:96
	ds_read_u16 v7, v20 offset:112
	ds_read_u16 v8, v20 offset:128
	ds_read_u16 v9, v20 offset:144
	ds_read_u16 v10, v20 offset:160
	ds_read_u16 v11, v20 offset:176
	ds_read_u16 v12, v20 offset:192
	ds_read_u16 v17, v20 offset:208
	ds_read_u16 v23, v20 offset:224
	ds_read_u16 v24, v20 offset:240
	s_mov_b32 m0, s30
	s_waitcnt lgkmcnt(0)
	s_waitcnt lgkmcnt(14)
	v_lshl_or_b32 v0, v0, 7, v21
	global_load_lds_dwordx4 v0, s[10:11]
	v_lshl_or_b32 v0, v1, 7, v21
	s_mov_b32 m0, s36
	s_mov_b32 s28, s13
	global_load_lds_dwordx4 v0, s[10:11]
	s_waitcnt lgkmcnt(0)
	v_lshl_or_b32 v0, v2, 7, v21
	s_mov_b32 m0, s37
	s_add_i32 s13, s13, s31
	global_load_lds_dwordx4 v0, s[10:11]
	v_lshl_or_b32 v0, v3, 7, v21
	s_mov_b32 m0, s38
	s_cmp_gt_u32 s13, 0x17fff
	global_load_lds_dwordx4 v0, s[10:11]
	v_lshl_or_b32 v0, v4, 7, v21
	s_mov_b32 m0, s39
	s_cselect_b64 s[26:27], -1, 0
	global_load_lds_dwordx4 v0, s[10:11]
	v_lshl_or_b32 v0, v5, 7, v21
	s_mov_b32 m0, s40
	s_cmp_lt_u32 s13, 0x18000
	global_load_lds_dwordx4 v0, s[10:11]
	v_lshl_or_b32 v0, v6, 7, v21
	s_mov_b32 m0, s41
	s_cselect_b32 s28, s13, s28
	global_load_lds_dwordx4 v0, s[10:11]
	v_lshl_or_b32 v0, v7, 7, v21
	s_mov_b32 m0, s42
	s_nop 0
	global_load_lds_dwordx4 v0, s[10:11]
	v_lshl_or_b32 v0, v8, 7, v21
	s_mov_b32 m0, s43
	s_nop 0
	global_load_lds_dwordx4 v0, s[10:11]
	v_lshl_or_b32 v0, v9, 7, v21
	s_mov_b32 m0, s44
	s_nop 0
	global_load_lds_dwordx4 v0, s[10:11]
	v_lshl_or_b32 v0, v10, 7, v21
	s_mov_b32 m0, s45
	v_lshl_or_b32 v10, v23, 7, v21
	global_load_lds_dwordx4 v0, s[10:11]
	v_lshl_or_b32 v0, v11, 7, v21
	s_mov_b32 m0, s46
	s_nop 0
	global_load_lds_dwordx4 v0, s[10:11]
	v_lshl_or_b32 v0, v12, 7, v21
	s_mov_b32 m0, s47
	v_lshl_or_b32 v12, s28, 7, v18
	global_load_lds_dwordx4 v0, s[10:11]
	v_lshl_or_b32 v0, v17, 7, v21
	s_mov_b32 m0, s48
	s_nop 0
	global_load_lds_dwordx4 v0, s[10:11]
	s_mov_b32 m0, s49
	v_lshl_or_b32 v8, v24, 7, v21
	global_load_lds_dwordx4 v10, s[10:11]
	s_mov_b32 m0, s50
	s_nop 0
	global_load_lds_dwordx4 v8, s[10:11]
	v_lshl_add_u64 v[8:9], v[12:13], 1, s[20:21]
	global_load_dword v23, v[8:9], off
	s_waitcnt vmcnt(9)
	ds_read_b128 v[36:39], v22
	ds_read_b128 v[40:43], v22 offset:16
	ds_read_b128 v[44:47], v22 offset:2048
	ds_read_b128 v[48:51], v22 offset:2064
	ds_read_b128 v[52:55], v22 offset:4096
	ds_read_b128 v[56:59], v22 offset:4112
	ds_read_b128 v[60:63], v22 offset:6144
	ds_read_b128 v[64:67], v22 offset:6160
	s_waitcnt lgkmcnt(7)
	v_mfma_f32_16x16x32_fp8_fp8 v[100:103], v[36:37], v[138:139], 0
	s_waitcnt lgkmcnt(5)
	v_mfma_f32_16x16x32_fp8_fp8 v[104:107], v[44:45], v[138:139], 0
	s_waitcnt lgkmcnt(3)
	v_mfma_f32_16x16x32_fp8_fp8 v[108:111], v[52:53], v[138:139], 0
	s_waitcnt lgkmcnt(1)
	v_mfma_f32_16x16x32_fp8_fp8 v[112:115], v[60:61], v[138:139], 0
	v_mfma_f32_16x16x32_fp8_fp8 v[100:103], v[38:39], v[140:141], v[100:103]
	v_mfma_f32_16x16x32_fp8_fp8 v[104:107], v[46:47], v[140:141], v[104:107]
	v_mfma_f32_16x16x32_fp8_fp8 v[108:111], v[54:55], v[140:141], v[108:111]
	v_mfma_f32_16x16x32_fp8_fp8 v[112:115], v[62:63], v[140:141], v[112:115]
	s_waitcnt lgkmcnt(0)
	v_mfma_f32_16x16x32_fp8_fp8 v[100:103], v[40:41], v[134:135], v[100:103]
	v_mfma_f32_16x16x32_fp8_fp8 v[104:107], v[48:49], v[134:135], v[104:107]
	v_mfma_f32_16x16x32_fp8_fp8 v[108:111], v[56:57], v[134:135], v[108:111]
	v_mfma_f32_16x16x32_fp8_fp8 v[112:115], v[64:65], v[134:135], v[112:115]
	v_mfma_f32_16x16x32_fp8_fp8 v[100:103], v[42:43], v[136:137], v[100:103]
	v_mfma_f32_16x16x32_fp8_fp8 v[104:107], v[50:51], v[136:137], v[104:107]
	v_mfma_f32_16x16x32_fp8_fp8 v[108:111], v[58:59], v[136:137], v[108:111]
	v_mfma_f32_16x16x32_fp8_fp8 v[112:115], v[66:67], v[136:137], v[112:115]
	s_waitcnt vmcnt(1)
	ds_read_b128 v[68:71], v22 offset:8192
	ds_read_b128 v[72:75], v22 offset:8208
	ds_read_b128 v[76:79], v22 offset:10240
	ds_read_b128 v[80:83], v22 offset:10256
	ds_read_b128 v[84:87], v22 offset:12288
	ds_read_b128 v[88:91], v22 offset:12304
	ds_read_b128 v[92:95], v22 offset:14336
	ds_read_b128 v[96:99], v22 offset:14352
	s_waitcnt lgkmcnt(7)
	v_mfma_f32_16x16x32_fp8_fp8 v[116:119], v[68:69], v[138:139], 0
	s_waitcnt lgkmcnt(5)
	v_mfma_f32_16x16x32_fp8_fp8 v[120:123], v[76:77], v[138:139], 0
	s_waitcnt lgkmcnt(3)
	v_mfma_f32_16x16x32_fp8_fp8 v[124:127], v[84:85], v[138:139], 0
	s_waitcnt lgkmcnt(1)
	v_mfma_f32_16x16x32_fp8_fp8 v[128:131], v[92:93], v[138:139], 0
	v_mfma_f32_16x16x32_fp8_fp8 v[116:119], v[70:71], v[140:141], v[116:119]
	v_mfma_f32_16x16x32_fp8_fp8 v[120:123], v[78:79], v[140:141], v[120:123]
	v_mfma_f32_16x16x32_fp8_fp8 v[124:127], v[86:87], v[140:141], v[124:127]
	v_mfma_f32_16x16x32_fp8_fp8 v[128:131], v[94:95], v[140:141], v[128:131]
	s_waitcnt lgkmcnt(0)
	v_mfma_f32_16x16x32_fp8_fp8 v[116:119], v[72:73], v[134:135], v[116:119]
	v_mfma_f32_16x16x32_fp8_fp8 v[120:123], v[80:81], v[134:135], v[120:123]
	v_mfma_f32_16x16x32_fp8_fp8 v[124:127], v[88:89], v[134:135], v[124:127]
	v_mfma_f32_16x16x32_fp8_fp8 v[128:131], v[96:97], v[134:135], v[128:131]
	v_mfma_f32_16x16x32_fp8_fp8 v[116:119], v[74:75], v[136:137], v[116:119]
	v_mfma_f32_16x16x32_fp8_fp8 v[120:123], v[82:83], v[136:137], v[120:123]
	v_mfma_f32_16x16x32_fp8_fp8 v[124:127], v[90:91], v[136:137], v[124:127]
	v_mfma_f32_16x16x32_fp8_fp8 v[128:131], v[98:99], v[136:137], v[128:131]
	s_and_saveexec_b64 s[28:29], s[8:9]
	v_mov_b32_e32 v17, v13
	s_nop 1
	v_lshl_add_u64 v[10:11], v[16:17], 1, s[24:25]
	v_cvt_pk_bf16_f32 v100, v100, v101
	v_cvt_pk_bf16_f32 v101, v102, v103
	global_store_dwordx2 v[10:11], v[100:101], off
	v_cvt_pk_bf16_f32 v104, v104, v105
	v_cvt_pk_bf16_f32 v105, v106, v107
	global_store_dwordx2 v[10:11], v[104:105], off offset:32
	v_cvt_pk_bf16_f32 v108, v108, v109
	v_cvt_pk_bf16_f32 v109, v110, v111
	global_store_dwordx2 v[10:11], v[108:109], off offset:64
	v_cvt_pk_bf16_f32 v112, v112, v113
	v_cvt_pk_bf16_f32 v113, v114, v115
	global_store_dwordx2 v[10:11], v[112:113], off offset:96
	v_cvt_pk_bf16_f32 v116, v116, v117
	v_cvt_pk_bf16_f32 v117, v118, v119
	global_store_dwordx2 v[10:11], v[116:117], off offset:128
	v_cvt_pk_bf16_f32 v120, v120, v121
	v_cvt_pk_bf16_f32 v121, v122, v123
	global_store_dwordx2 v[10:11], v[120:121], off offset:160
	v_cvt_pk_bf16_f32 v124, v124, v125
	v_cvt_pk_bf16_f32 v125, v126, v127
	global_store_dwordx2 v[10:11], v[124:125], off offset:192
	v_cvt_pk_bf16_f32 v128, v128, v129
	v_cvt_pk_bf16_f32 v129, v130, v131
	global_store_dwordx2 v[10:11], v[128:129], off offset:224
	s_branch .LBB0_372
